# speedup vs baseline: 1.0022x; 1.0021x over previous
; DEVI void finishSM(f32x16& p0, f32x16& p1, float alpha, float& l_reg, bf16x8& pa0, bf16x8& pa1, bf16x8& pa2, bf16x8& pa3) {
; #pragma unroll
;   for (int r = 0; r < 16; ++r) p1[r] = __builtin_amdgcn_exp2f(p1[r]);
;   float ps = 0;
; #pragma unroll
;   for (int r = 0; r < 16; ++r) ps += p0[r];
; #pragma unroll
;   for (int r = 0; r < 16; ++r) ps += p1[r];
;   { auto rr = __builtin_amdgcn_permlane32_swap(__float_as_uint(ps), __float_as_uint(ps), false, false);
;     ps = __uint_as_float(rr[0]) + __uint_as_float(rr[1]); }
;   l_reg = l_reg * alpha + ps;
;     ...
;   PK4(p0, 0, pa0); PK4(p0, 8, pa1); PK4(p1, 0, pa2); PK4(p1, 8, pa3);
; DEVI void qkt(f32x16& p0, f32x16& p1, const char* Ks, const char* Rs, const bf16x8* qr, const char* Qrs, int r32, int hi) {
;   p0 = f32x16{}; p1 = f32x16{};
; #pragma unroll
;   for (int d0 = 0; d0 < 8; ++d0) { int cb = (d0 * 16 + hi * 8) * 2;
;     bf16x8 b0 = *reinterpret_cast<const bf16x8*>(Ks + KSWZ(r32, cb));
;     bf16x8 b1 = *reinterpret_cast<const bf16x8*>(Ks + KSWZ(32 + r32, cb));
;     p0 = __builtin_amdgcn_mfma_f32_32x32x16_bf16(b0, qr[d0], p0, 0, 0, 0);
;     p1 = __builtin_amdgcn_mfma_f32_32x32x16_bf16(b1, qr[d0], p1, 0, 0, 0); }
; #pragma unroll
;   for (int d0 = 0; d0 < 4; ++d0) { int cb = (d0 * 16 + hi * 8) * 2;
;     bf16x8 b0 = *reinterpret_cast<const bf16x8*>(Rs + RSWZ(r32, cb));
;     bf16x8 b1 = *reinterpret_cast<const bf16x8*>(Rs + RSWZ(32 + r32, cb));
;     bf16x8 qf = *reinterpret_cast<const bf16x8*>(Qrs + RSWZ(r32, cb));
;     p0 = __builtin_amdgcn_mfma_f32_32x32x16_bf16(b0, qf, p0, 0, 0, 0);
;     p1 = __builtin_amdgcn_mfma_f32_32x32x16_bf16(b1, qf, p1, 0, 0, 0); }
.LBB0_981:
	global_load_dwordx4 v[128:131], v168, s[36:37] offset:3072
	v_add_u32_e32 v64, 0x20000, v168
	global_load_dwordx4 v[132:135], v64, s[36:37] offset:3072
	global_load_dwordx4 v[136:139], v166, s[36:37] offset:3072
	ds_read_b128 v[64:67], v187 offset:49152
	v_exp_f32_e32 v242, v80
	s_waitcnt lgkmcnt(0)
	v_mfma_f32_32x32x16_bf16 v[64:79], v[64:67], v[96:99], 0
	ds_read_b128 v[82:85], v187 offset:57344
	v_exp_f32_e32 v245, v81
	s_waitcnt lgkmcnt(0)
	v_mfma_f32_32x32x16_bf16 v[80:95], v[82:85], v[96:99], 0
	ds_read_b128 v[238:241], v188 offset:49152
	v_exp_f32_e32 v248, v152
	s_waitcnt lgkmcnt(0)
	v_mfma_f32_32x32x16_bf16 v[64:79], v[238:241], v[100:103], v[64:79]
	ds_read_b128 v[238:241], v188 offset:57344
	v_exp_f32_e32 v251, v153
	s_waitcnt lgkmcnt(0)
	v_mfma_f32_32x32x16_bf16 v[80:95], v[238:241], v[100:103], v[80:95]
	ds_read_b128 v[238:241], v189 offset:49152
	v_add_f32_e32 v152, 0, v231
	v_add_f32_e32 v152, v235, v152
	v_add_f32_e32 v152, v230, v152
	v_exp_f32_e32 v252, v150
	s_waitcnt lgkmcnt(0)
	v_mfma_f32_32x32x16_bf16 v[64:79], v[238:241], v[104:107], v[64:79]
	ds_read_b128 v[238:241], v189 offset:57344
	v_add_f32_e32 v150, v232, v152
	v_add_f32_e32 v150, v233, v150
	v_add_f32_e32 v221, v236, v150
	v_exp_f32_e32 v253, v151
	s_waitcnt lgkmcnt(0)
	v_mfma_f32_32x32x16_bf16 v[80:95], v[238:241], v[104:107], v[80:95]
	ds_read_b128 v[150:153], v190 offset:49152
	v_add_f32_e32 v221, v234, v221
	v_add_f32_e32 v221, v237, v221
	v_add_f32_e32 v221, v156, v221
	v_exp_f32_e32 v209, v148
	s_waitcnt lgkmcnt(0)
	v_mfma_f32_32x32x16_bf16 v[64:79], v[150:153], v[108:111], v[64:79]
	ds_read_b128 v[150:153], v190 offset:57344
	v_add_f32_e32 v148, v157, v221
	v_add_f32_e32 v148, v158, v148
	v_add_f32_e32 v221, v159, v148
	v_exp_f32_e32 v210, v149
	s_waitcnt lgkmcnt(0)
	v_mfma_f32_32x32x16_bf16 v[80:95], v[150:153], v[108:111], v[80:95]
	ds_read_b128 v[148:151], v191 offset:49152
	v_add_f32_e32 v152, v228, v221
	v_add_f32_e32 v152, v229, v152
	v_add_f32_e32 v152, v154, v152
	v_exp_f32_e32 v211, v142
	s_waitcnt lgkmcnt(0)
	v_mfma_f32_32x32x16_bf16 v[64:79], v[148:151], v[112:115], v[64:79]
	ds_read_b128 v[148:151], v191 offset:57344
	v_add_f32_e32 v142, v155, v152
	v_add_f32_e32 v142, v242, v142
	v_add_f32_e32 v142, v245, v142
	v_exp_f32_e32 v212, v143
	s_waitcnt lgkmcnt(0)
	v_mfma_f32_32x32x16_bf16 v[80:95], v[148:151], v[112:115], v[80:95]
	ds_read_b128 v[148:151], v192 offset:49152
	v_add_f32_e32 v142, v248, v142
	v_add_f32_e32 v142, v251, v142
	v_add_f32_e32 v142, v252, v142
	v_exp_f32_e32 v214, v146
	s_waitcnt lgkmcnt(0)
	v_mfma_f32_32x32x16_bf16 v[64:79], v[148:151], v[116:119], v[64:79]
	ds_read_b128 v[148:151], v192 offset:57344
	v_add_f32_e32 v142, v253, v142
	v_add_f32_e32 v142, v209, v142
	v_add_f32_e32 v142, v210, v142
	v_exp_f32_e32 v215, v147
	s_waitcnt lgkmcnt(0)
	v_mfma_f32_32x32x16_bf16 v[80:95], v[148:151], v[116:119], v[80:95]
	ds_read_b128 v[146:149], v193 offset:49152
	v_add_f32_e32 v142, v211, v142
	v_add_f32_e32 v142, v212, v142
	v_add_f32_e32 v142, v214, v142
	v_exp_f32_e32 v216, v140
	s_waitcnt lgkmcnt(0)
	v_mfma_f32_32x32x16_bf16 v[64:79], v[146:149], v[120:123], v[64:79]
	ds_read_b128 v[146:149], v193 offset:57344
	v_add_f32_e32 v142, v215, v142
	v_cvt_pk_bf16_f32 v140, v231, v235
	v_add_f32_e32 v142, v216, v142
	v_exp_f32_e32 v217, v141
	s_waitcnt lgkmcnt(0)
	v_mfma_f32_32x32x16_bf16 v[80:95], v[146:149], v[120:123], v[80:95]
	ds_read_b128 v[146:149], v194 offset:49152
	v_add_f32_e32 v143, v217, v142
	v_cvt_pk_bf16_f32 v141, v230, v232
	v_cvt_pk_bf16_f32 v142, v233, v236
	v_exp_f32_e32 v218, v144
	s_waitcnt lgkmcnt(0)
	v_mfma_f32_32x32x16_bf16 v[64:79], v[146:149], v[124:127], v[64:79]
	ds_read_b128 v[146:149], v194 offset:57344
	v_add_f32_e32 v144, v218, v143
	v_cvt_pk_bf16_f32 v143, v234, v237
	v_permlane32_swap_b32_e32 v140, v142
	v_exp_f32_e32 v219, v145
	s_waitcnt lgkmcnt(0)
	v_mfma_f32_32x32x16_bf16 v[80:95], v[146:149], v[124:127], v[80:95]
	ds_read_b128 v[148:151], v195 offset:8192
	v_add_f32_e32 v204, v219, v144
	v_permlane32_swap_b32_e32 v141, v143
	v_mov_b32_e32 v221, v204
	ds_read_b128 v[230:233], v195 offset:12288
	v_cvt_pk_bf16_f32 v144, v156, v157
	v_cvt_pk_bf16_f32 v145, v158, v159
	ds_read_b128 v[156:159], v196
	v_cvt_pk_bf16_f32 v146, v228, v229
	ds_read_b128 v[234:237], v198
	s_waitcnt lgkmcnt(1)
	v_mfma_f32_32x32x16_bf16 v[80:95], v[230:233], v[156:159], v[80:95]
	ds_read_b128 v[228:231], v197 offset:12288
	s_waitcnt lgkmcnt(0)
	v_mfma_f32_32x32x16_bf16 v[80:95], v[228:231], v[234:237], v[80:95]
	ds_read_b128 v[228:231], v199 offset:12288
	ds_read_b128 v[238:241], v200
	s_waitcnt lgkmcnt(0)
	v_mfma_f32_32x32x16_bf16 v[80:95], v[228:231], v[238:241], v[80:95]
	v_permlane32_swap_b32_e32 v204, v221
	v_cvt_pk_bf16_f32 v147, v154, v155
	v_permlane32_swap_b32_e32 v144, v146
	ds_read_b128 v[228:231], v201 offset:12288
	v_mfma_f32_32x32x16_bf16 v[64:79], v[148:151], v[156:159], v[64:79]
	v_permlane32_swap_b32_e32 v145, v147
	ds_read_b128 v[148:151], v197 offset:8192
	v_cvt_pk_bf16_f32 v155, v218, v219
	ds_read_b128 v[156:159], v202
	s_waitcnt lgkmcnt(1)
	v_mfma_f32_32x32x16_bf16 v[64:79], v[148:151], v[234:237], v[64:79]
	ds_read_b128 v[148:151], v199 offset:8192
	v_cvt_pk_bf16_f32 v154, v216, v217
	s_waitcnt lgkmcnt(0)
	v_mfma_f32_32x32x16_bf16 v[64:79], v[148:151], v[238:241], v[64:79]
	ds_read_b128 v[150:153], v201 offset:8192
	s_waitcnt lgkmcnt(0)
; #define SBAR() __builtin_amdgcn_sched_barrier(0)
; #define SLOAD_V(k0) do { const char* vb_ = (const char*)VTh + (size_t)(k0) * 2; const char* vb2_ = vb_ + vhalf;                \
;     vs0 = *reinterpret_cast<const bf16x8*>(vb_ + vo_v); vs1 = *reinterpret_cast<const bf16x8*>(vb2_ + vo_v); } while (0)
; #define SWRITE_KR(b) do { int kc = sc * 2; *(bf16x8*)(K_lds + (b) * SHM_K + KSWZ(sr, kc)) = ks0; *(bf16x8*)(K_lds + (b) * SHM_K + KSWZ(32 + sr, kc)) = ks1; \
;     *(bf16x8*)(R_lds + (b) * SHM_R + RSWZ(rr_, rc_ * 2)) = rs0; } while (0)
; #define SWRITE_V(b) do { *(bf16x8*)(V_lds + (b) * SHM_V + RSWZ(vd, vc * 16)) = vs0; *(bf16x8*)(V_lds + (b) * SHM_V + RSWZ(vd + 64, vc * 16)) = vs1; } while (0)
; #define SWAIT() asm volatile("s_waitcnt vmcnt(0)" ::: "memory")
; #define RESC(a) do { if (__any((a) < 1.f)) { if (hi == 0) al_l[r32] = (a); asm volatile("s_waitcnt lgkmcnt(0)" ::: "memory"); \
;     _Pragma("unroll") for (int d = 0; d < 4; ++d) _Pragma("unroll") for (int r = 0; r < 16; ++r) o[d][r] *= al_l[crow(r, hi)]; } } while (0)
; DEVI void attn_item(const u16* __restrict__ Qb, const u16* __restrict__ KNh, const u16* __restrict__ VTh, int Lpad, const u16* __restrict__ KRb,
;                     const u16* __restrict__ SZb, u16* __restrict__ AOb, int NT, char* lds, const int wid_s_) {
;     ...
;     SLOAD_V((j + 1) * 64); SBAR();
;     pv_d0(o, V_lds, r32, hi, pa0, pa1, pa2, pa3); partialSM(pB0, pB1, m_reg, mnB, alB);
;     SWRITE_KR(0);
;     __syncthreads(); SWAIT(); SWRITE_V(0);
;     RESC(alB); __syncthreads();
	v_mfma_f32_32x32x16_bf16 v[64:79], v[150:153], v[156:159], v[64:79]
	v_cvt_pk_bf16_f32 v153, v214, v215
	v_cvt_pk_bf16_f32 v152, v211, v212
	v_cvt_pk_bf16_f32 v151, v209, v210
	v_cvt_pk_bf16_f32 v149, v248, v251
	s_nop 1
	v_permlane32_swap_b32_e32 v149, v151
	v_cvt_pk_bf16_f32 v148, v242, v245
	v_mfma_f32_32x32x16_bf16 v[80:95], v[228:231], v[156:159], v[80:95]
	v_cvt_pk_bf16_f32 v150, v252, v253
	s_nop 1
	v_permlane32_swap_b32_e32 v148, v150
	v_permlane32_swap_b32_e32 v152, v154
	v_permlane32_swap_b32_e32 v153, v155
	global_load_dwordx4 v[228:231], v162, s[36:37] offset:3328
	global_load_dwordx4 v[232:235], v164, s[36:37] offset:3328
	ds_read_b128 v[236:239], v177
	ds_read_b128 v[240:243], v161
	ds_read_b128 v[244:247], v180
	ds_read_b128 v[248:251], v179
	s_waitcnt lgkmcnt(3)
	v_mfma_f32_32x32x16_bf16 v[16:31], v[140:143], v[236:239], v[16:31]
	ds_read_b128 v[236:239], v177 offset:4096
	s_waitcnt lgkmcnt(3)
	v_mfma_f32_32x32x16_bf16 v[16:31], v[144:147], v[240:243], v[16:31]
	ds_read_b128 v[240:243], v161 offset:4096
	s_waitcnt lgkmcnt(1)
	v_mfma_f32_32x32x16_bf16 v[48:63], v[140:143], v[236:239], v[48:63]
	ds_read_b128 v[236:239], v177 offset:8192
	v_mfma_f32_32x32x16_bf16 v[16:31], v[148:151], v[244:247], v[16:31]
	ds_read_b128 v[244:247], v180 offset:4096
	s_waitcnt lgkmcnt(2)
	v_mfma_f32_32x32x16_bf16 v[48:63], v[144:147], v[240:243], v[48:63]
	ds_read_b128 v[240:243], v161 offset:8192
	s_waitcnt lgkmcnt(2)
	v_mfma_f32_32x32x16_bf16 v[32:47], v[140:143], v[236:239], v[32:47]
	ds_read_b128 v[236:239], v177 offset:12288
	v_mfma_f32_32x32x16_bf16 v[16:31], v[152:155], v[248:251], v[16:31]
	ds_read_b128 v[248:251], v179 offset:4096
	s_waitcnt lgkmcnt(3)
	v_mfma_f32_32x32x16_bf16 v[48:63], v[148:151], v[244:247], v[48:63]
	ds_read_b128 v[244:247], v180 offset:8192
	s_waitcnt lgkmcnt(3)
	v_mfma_f32_32x32x16_bf16 v[32:47], v[144:147], v[240:243], v[32:47]
	ds_read_b128 v[240:243], v161 offset:12288
	s_waitcnt lgkmcnt(3)
	v_mfma_f32_32x32x16_bf16 v[0:15], v[140:143], v[236:239], v[0:15]
	v_max_f32_e32 v140, v65, v65
	v_max_f32_e32 v141, v64, v64
	v_max_f32_e32 v140, v141, v140
	v_max3_f32 v140, v140, v66, v67
	v_max3_f32 v140, v140, v68, v69
	v_max3_f32 v140, v140, v70, v71
	v_max3_f32 v140, v140, v72, v73
	v_max3_f32 v140, v140, v74, v75
	v_max3_f32 v140, v140, v76, v77
	s_waitcnt lgkmcnt(2)
	v_mfma_f32_32x32x16_bf16 v[48:63], v[152:155], v[248:251], v[48:63]
	ds_read_b128 v[248:251], v179 offset:8192
	v_max3_f32 v140, v140, v78, v79
	v_max3_f32 v140, v140, v80, v81
	v_max3_f32 v140, v140, v82, v83
	v_max3_f32 v140, v140, v84, v85
	v_max3_f32 v140, v140, v86, v87
	v_max3_f32 v140, v140, v88, v89
	s_waitcnt lgkmcnt(2)
	v_mfma_f32_32x32x16_bf16 v[32:47], v[148:151], v[244:247], v[32:47]
	ds_read_b128 v[244:247], v180 offset:12288
	v_max3_f32 v140, v140, v90, v91
	v_max3_f32 v140, v140, v92, v93
	v_max3_f32 v140, v140, v94, v95
	v_mov_b32_e32 v141, v140
	s_nop 1
	v_permlane32_swap_b32_e32 v140, v141
	s_waitcnt lgkmcnt(2)
	v_mfma_f32_32x32x16_bf16 v[0:15], v[144:147], v[240:243], v[0:15]
	v_max_f32_e32 v141, v141, v141
	v_max_f32_e32 v140, v140, v140
	v_max_f32_e32 v140, v140, v141
	v_sub_f32_e32 v141, v140, v222
	v_cmp_ge_f32_e32 vcc, s91, v141
	v_max_f32_e32 v141, v222, v222
	v_max_f32_e32 v140, v141, v140
	s_waitcnt lgkmcnt(1)
	v_mfma_f32_32x32x16_bf16 v[32:47], v[152:155], v[248:251], v[32:47]
	ds_read_b128 v[248:251], v179 offset:12288
	v_sub_f32_e32 v141, v222, v140
	v_mul_f32_e32 v141, 0x3dd53b94, v141
	v_exp_f32_e32 v141, v141
	s_cmp_eq_u64 vcc, exec
	s_cselect_b64 s[8:9], -1, 0
	s_waitcnt vmcnt(2)
	ds_write_b128 v184, v[128:131] offset:32768
	s_waitcnt lgkmcnt(2)
	v_mfma_f32_32x32x16_bf16 v[0:15], v[148:151], v[244:247], v[0:15]
	ds_write_b128 v184, v[132:135] offset:40960
	ds_write_b128 v186, v[136:139]
	s_waitcnt lgkmcnt(0)
	s_barrier
	s_waitcnt vmcnt(0)
	v_cndmask_b32_e64 v224, v141, 1.0, s[8:9]
	v_mfma_f32_32x32x16_bf16 v[0:15], v[152:155], v[248:251], v[0:15]
	v_cmp_gt_f32_e32 vcc, 1.0, v224
	ds_write_b128 v185, v[228:231]
	ds_write_b128 v185, v[232:235] offset:8192
	s_cbranch_vccnz .Lresc_a
.LBB0_985:
	v_cndmask_b32_e64 v222, v140, v222, s[8:9]
	v_mul_f32_e32 v152, 0xbdd53b94, v222
	v_fmamk_f32 v66, v66, 0x3dd53b94, v152
	v_fmamk_f32 v67, v67, 0x3dd53b94, v152
	v_exp_f32_e32 v141, v66
	v_add_u32_e32 v66, 0x40000, v168
	v_fmamk_f32 v68, v68, 0x3dd53b94, v152
	v_exp_f32_e32 v236, v67
	v_fmamk_f32 v69, v69, 0x3dd53b94, v152
	v_exp_f32_e32 v237, v68
	v_add_u32_e32 v68, 0x60000, v168
	v_fmamk_f32 v128, v64, 0x3dd53b94, v152
	v_exp_f32_e32 v238, v69
	v_exp_f32_e32 v140, v128
	s_waitcnt lgkmcnt(0)
	s_barrier
; DEVI void partialSM(f32x16& p0, f32x16& p1, float& m_reg, float& mn, float& alpha) {
;     ...
;   for (int r = 0; r < 16; ++r) p0[r] = fmaf(p0[r], C, mnC);
; #pragma unroll
;   for (int r = 0; r < 16; ++r) p1[r] = fmaf(p1[r], C, mnC);
; #pragma unroll
;   for (int r = 0; r < 16; ++r) p0[r] = __builtin_amdgcn_exp2f(p0[r]);
; }
; DEVI void finishSM(f32x16& p0, f32x16& p1, float alpha, float& l_reg, bf16x8& pa0, bf16x8& pa1, bf16x8& pa2, bf16x8& pa3) {
; #pragma unroll
;   for (int r = 0; r < 16; ++r) p1[r] = __builtin_amdgcn_exp2f(p1[r]);
;   float ps = 0;
; #pragma unroll
;   for (int r = 0; r < 16; ++r) ps += p0[r];
; #pragma unroll
;   for (int r = 0; r < 16; ++r) ps += p1[r];
;   { auto rr = __builtin_amdgcn_permlane32_swap(__float_as_uint(ps), __float_as_uint(ps), false, false);
;     ps = __uint_as_float(rr[0]) + __uint_as_float(rr[1]); }
;   l_reg = l_reg * alpha + ps;
;     ...
;   PK4(p0, 0, pa0); PK4(p0, 8, pa1); PK4(p1, 0, pa2); PK4(p1, 8, pa3);
; DEVI void qkt(f32x16& p0, f32x16& p1, const char* Ks, const char* Rs, const bf16x8* qr, const char* Qrs, int r32, int hi) {
;   p0 = f32x16{}; p1 = f32x16{};
; #pragma unroll
;   for (int d0 = 0; d0 < 8; ++d0) { int cb = (d0 * 16 + hi * 8) * 2;
;     bf16x8 b0 = *reinterpret_cast<const bf16x8*>(Ks + KSWZ(r32, cb));
;     bf16x8 b1 = *reinterpret_cast<const bf16x8*>(Ks + KSWZ(32 + r32, cb));
;     p0 = __builtin_amdgcn_mfma_f32_32x32x16_bf16(b0, qr[d0], p0, 0, 0, 0);
;     p1 = __builtin_amdgcn_mfma_f32_32x32x16_bf16(b1, qr[d0], p1, 0, 0, 0); }
	global_load_dwordx4 v[128:131], v66, s[36:37] offset:3072
	v_add_u32_e32 v66, 0x2000, v166
	global_load_dwordx4 v[132:135], v68, s[36:37] offset:3072
	global_load_dwordx4 v[136:139], v66, s[36:37] offset:3072
	v_fmamk_f32 v74, v74, 0x3dd53b94, v152
	v_fmamk_f32 v75, v75, 0x3dd53b94, v152
	v_exp_f32_e32 v228, v74
	v_exp_f32_e32 v229, v75
	v_fmamk_f32 v65, v65, 0x3dd53b94, v152
	v_fmamk_f32 v70, v70, 0x3dd53b94, v152
	v_fmamk_f32 v71, v71, 0x3dd53b94, v152
	v_fmamk_f32 v72, v72, 0x3dd53b94, v152
	v_fmamk_f32 v73, v73, 0x3dd53b94, v152
	v_fmamk_f32 v76, v76, 0x3dd53b94, v152
	v_fmamk_f32 v77, v77, 0x3dd53b94, v152
	v_fmamk_f32 v78, v78, 0x3dd53b94, v152
	v_fmamk_f32 v79, v79, 0x3dd53b94, v152
	v_fmamk_f32 v64, v80, 0x3dd53b94, v152
	v_fmamk_f32 v80, v81, 0x3dd53b94, v152
	v_fmamk_f32 v241, v82, 0x3dd53b94, v152
	v_fmamk_f32 v145, v83, 0x3dd53b94, v152
	v_fmamk_f32 v144, v84, 0x3dd53b94, v152
	v_fmamk_f32 v143, v85, 0x3dd53b94, v152
	v_fmamk_f32 v142, v86, 0x3dd53b94, v152
	v_fmamk_f32 v239, v87, 0x3dd53b94, v152
	v_fmamk_f32 v154, v88, 0x3dd53b94, v152
	v_fmamk_f32 v150, v89, 0x3dd53b94, v152
	v_fmamk_f32 v146, v90, 0x3dd53b94, v152
	v_fmamk_f32 v147, v91, 0x3dd53b94, v152
	v_fmamk_f32 v148, v92, 0x3dd53b94, v152
	v_exp_f32_e32 v240, v65
	v_exp_f32_e32 v234, v70
	v_exp_f32_e32 v235, v71
	v_exp_f32_e32 v232, v72
	v_exp_f32_e32 v233, v73
	v_exp_f32_e32 v230, v76
	v_exp_f32_e32 v231, v77
	v_exp_f32_e32 v153, v78
	v_exp_f32_e32 v155, v79
	v_fmamk_f32 v149, v93, 0x3dd53b94, v152
	v_fmamk_f32 v151, v94, 0x3dd53b94, v152
	v_fmac_f32_e32 v152, 0x3dd53b94, v95
	ds_read_b128 v[66:69], v187 offset:32768
	v_add_f32_e32 v65, 0, v140
	v_add_f32_e32 v65, v240, v65
	v_add_f32_e32 v81, v141, v65
	v_exp_f32_e32 v209, v64
	s_cmp_eq_u32 s4, s2
	s_cselect_b64 vcc, -1, 0
	s_waitcnt lgkmcnt(0)
	v_mfma_f32_32x32x16_bf16 v[64:79], v[66:69], v[96:99], 0
	ds_read_b128 v[82:85], v187 offset:40960
	v_add_f32_e32 v81, v236, v81
	v_add_f32_e32 v81, v237, v81
	v_add_f32_e32 v210, v238, v81
	v_exp_f32_e32 v211, v80
	s_waitcnt lgkmcnt(0)
	v_mfma_f32_32x32x16_bf16 v[80:95], v[82:85], v[96:99], 0
	ds_read_b128 v[170:173], v188 offset:32768
	v_add_f32_e32 v210, v234, v210
	v_add_f32_e32 v210, v235, v210
	v_add_f32_e32 v210, v232, v210
	v_exp_f32_e32 v212, v241
	s_waitcnt lgkmcnt(0)
	v_mfma_f32_32x32x16_bf16 v[64:79], v[170:173], v[100:103], v[64:79]
	ds_read_b128 v[170:173], v188 offset:40960
	v_add_f32_e32 v210, v233, v210
	v_add_f32_e32 v210, v228, v210
	v_add_f32_e32 v210, v229, v210
	v_exp_f32_e32 v214, v145
	s_waitcnt lgkmcnt(0)
	v_mfma_f32_32x32x16_bf16 v[80:95], v[170:173], v[100:103], v[80:95]
	ds_read_b128 v[170:173], v189 offset:32768
	v_add_f32_e32 v145, v230, v210
	v_add_f32_e32 v145, v231, v145
	v_add_f32_e32 v145, v153, v145
	v_exp_f32_e32 v210, v144
	s_waitcnt lgkmcnt(0)
	v_mfma_f32_32x32x16_bf16 v[64:79], v[170:173], v[104:107], v[64:79]
	ds_read_b128 v[170:173], v189 offset:40960
	v_add_f32_e32 v144, v155, v145
	v_add_f32_e32 v144, v209, v144
	v_add_f32_e32 v144, v211, v144
	v_exp_f32_e32 v215, v143
	s_waitcnt lgkmcnt(0)
	v_mfma_f32_32x32x16_bf16 v[80:95], v[170:173], v[104:107], v[80:95]
	ds_read_b128 v[170:173], v190 offset:32768
	v_add_f32_e32 v143, v212, v144
	v_add_f32_e32 v143, v214, v143
	v_add_f32_e32 v216, v210, v143
	v_exp_f32_e32 v217, v142
	s_waitcnt lgkmcnt(0)
	v_mfma_f32_32x32x16_bf16 v[64:79], v[170:173], v[108:111], v[64:79]
	ds_read_b128 v[142:145], v190 offset:40960
	v_add_f32_e32 v170, v215, v216
	v_cvt_pk_bf16_f32 v140, v140, v240
	v_add_f32_e32 v216, v217, v170
	v_exp_f32_e32 v218, v239
	s_waitcnt lgkmcnt(0)
	v_mfma_f32_32x32x16_bf16 v[80:95], v[142:145], v[108:111], v[80:95]
	ds_read_b128 v[170:173], v191 offset:32768
	v_cvt_pk_bf16_f32 v141, v141, v236
	v_cvt_pk_bf16_f32 v142, v237, v238
	v_add_f32_e32 v143, v218, v216
	v_exp_f32_e32 v154, v154
	s_waitcnt lgkmcnt(0)
	v_mfma_f32_32x32x16_bf16 v[64:79], v[170:173], v[112:115], v[64:79]
	ds_read_b128 v[170:173], v191 offset:40960
	v_add_f32_e32 v144, v154, v143
	v_cvt_pk_bf16_f32 v143, v234, v235
	v_permlane32_swap_b32_e32 v140, v142
	v_exp_f32_e32 v216, v150
	s_waitcnt lgkmcnt(0)
	v_mfma_f32_32x32x16_bf16 v[80:95], v[170:173], v[112:115], v[80:95]
	ds_read_b128 v[170:173], v192 offset:32768
	v_add_f32_e32 v145, v216, v144
	v_permlane32_swap_b32_e32 v141, v143
	v_cvt_pk_bf16_f32 v144, v232, v233
	v_exp_f32_e32 v219, v146
	s_waitcnt lgkmcnt(0)
	v_mfma_f32_32x32x16_bf16 v[64:79], v[170:173], v[116:119], v[64:79]
	ds_read_b128 v[170:173], v192 offset:40960
	v_add_f32_e32 v150, v219, v145
	v_cvt_pk_bf16_f32 v145, v228, v229
	v_cvt_pk_bf16_f32 v146, v230, v231
	v_exp_f32_e32 v236, v147
	s_waitcnt lgkmcnt(0)
	v_mfma_f32_32x32x16_bf16 v[80:95], v[170:173], v[116:119], v[80:95]
	ds_read_b128 v[170:173], v193 offset:32768
	v_add_f32_e32 v150, v236, v150
	v_cvt_pk_bf16_f32 v147, v153, v155
	v_permlane32_swap_b32_e32 v144, v146
	v_exp_f32_e32 v155, v148
	s_waitcnt lgkmcnt(0)
	v_mfma_f32_32x32x16_bf16 v[64:79], v[170:173], v[120:123], v[64:79]
	ds_read_b128 v[170:173], v193 offset:40960
	v_add_f32_e32 v150, v155, v150
	v_permlane32_swap_b32_e32 v145, v147
	v_cvt_pk_bf16_f32 v148, v209, v211
	v_exp_f32_e32 v209, v149
	s_waitcnt lgkmcnt(0)
	v_mfma_f32_32x32x16_bf16 v[80:95], v[170:173], v[120:123], v[80:95]
	ds_read_b128 v[170:173], v194 offset:32768
	v_add_f32_e32 v153, v209, v150
	v_cvt_pk_bf16_f32 v149, v212, v214
	v_cvt_pk_bf16_f32 v150, v210, v215
	v_exp_f32_e32 v210, v151
	s_waitcnt lgkmcnt(0)
	v_mfma_f32_32x32x16_bf16 v[64:79], v[170:173], v[124:127], v[64:79]
	ds_read_b128 v[170:173], v194 offset:40960
	v_add_f32_e32 v153, v210, v153
	v_cvt_pk_bf16_f32 v151, v217, v218
	v_permlane32_swap_b32_e32 v148, v150
	v_exp_f32_e32 v211, v152
	s_waitcnt lgkmcnt(0)
; #define SBAR() __builtin_amdgcn_sched_barrier(0)
; #define SGB_QK() _Pragma("unroll") for (int g_ = 0; g_ < 24; ++g_) { __builtin_amdgcn_sched_group_barrier(0x008, 1, 0); __builtin_amdgcn_sched_group_barrier(0x100, 1, 0); \
;     __builtin_amdgcn_sched_group_barrier(0x002, 3, 0); __builtin_amdgcn_sched_group_barrier(0x400, 1, 0); }
; #define SLOAD_V(k0) do { const char* vb_ = (const char*)VTh + (size_t)(k0) * 2; const char* vb2_ = vb_ + vhalf;                \
;     vs0 = *reinterpret_cast<const bf16x8*>(vb_ + vo_v); vs1 = *reinterpret_cast<const bf16x8*>(vb2_ + vo_v); } while (0)
; #define SWRITE_KR(b) do { int kc = sc * 2; *(bf16x8*)(K_lds + (b) * SHM_K + KSWZ(sr, kc)) = ks0; *(bf16x8*)(K_lds + (b) * SHM_K + KSWZ(32 + sr, kc)) = ks1; \
;     *(bf16x8*)(R_lds + (b) * SHM_R + RSWZ(rr_, rc_ * 2)) = rs0; } while (0)
; #define SWRITE_V(b) do { *(bf16x8*)(V_lds + (b) * SHM_V + RSWZ(vd, vc * 16)) = vs0; *(bf16x8*)(V_lds + (b) * SHM_V + RSWZ(vd + 64, vc * 16)) = vs1; } while (0)
; #define SWAIT() asm volatile("s_waitcnt vmcnt(0)" ::: "memory")
; #define RESC(a) do { if (__any((a) < 1.f)) { if (hi == 0) al_l[r32] = (a); asm volatile("s_waitcnt lgkmcnt(0)" ::: "memory"); \
;     _Pragma("unroll") for (int d = 0; d < 4; ++d) _Pragma("unroll") for (int r = 0; r < 16; ++r) o[d][r] *= al_l[crow(r, hi)]; } } while (0)
; DEVI void mask_tile(f32x16& p0, f32x16& p1, bool nv16) {
; #pragma unroll
;   for (int r = 0; r < 16; ++r) { if (!(nv16 && r < 8)) p0[r] = -1e30f; p1[r] = -1e30f; }
; }
; DEVI void attn_item(const u16* __restrict__ Qb, const u16* __restrict__ KNh, const u16* __restrict__ VTh, int Lpad, const u16* __restrict__ KRb,
;                     const u16* __restrict__ SZb, u16* __restrict__ AOb, int NT, char* lds, const int wid_s_) {
;     ...
;     if (j + 1 == NT - 2) mask_tile(pA0, pA1, true);
;     finishSM(pB0, pB1, alB, l_reg, pa0, pa1, pa2, pa3); SGB_QK(); SBAR();
;     SLOAD_V((j + 2) * 64); SBAR();
;     pv_d0(o, V_lds + SHM_V, r32, hi, pa0, pa1, pa2, pa3); partialSM(pA0, pA1, m_reg, mnA, alA);
;     SWRITE_KR(1);
;     __syncthreads(); SWAIT(); SWRITE_V(1);
;     RESC(alA); __syncthreads();
	v_mfma_f32_32x32x16_bf16 v[80:95], v[170:173], v[124:127], v[80:95]
	ds_read_b128 v[228:231], v195
	v_add_f32_e32 v170, v211, v153
	v_mov_b32_e32 v171, v170
	v_permlane32_swap_b32_e32 v149, v151
	ds_read_b128 v[232:235], v195 offset:4096
	v_permlane32_swap_b32_e32 v170, v171
	v_cvt_pk_bf16_f32 v152, v154, v216
	v_cvt_pk_bf16_f32 v153, v219, v236
	ds_read_b128 v[236:239], v196
	s_waitcnt lgkmcnt(0)
	v_mfma_f32_32x32x16_bf16 v[64:79], v[228:231], v[236:239], v[64:79]
	ds_read_b128 v[228:231], v197
	v_mfma_f32_32x32x16_bf16 v[80:95], v[232:235], v[236:239], v[80:95]
	ds_read_b128 v[240:243], v198
	ds_read_b128 v[232:235], v202
	ds_read_b128 v[236:239], v199 offset:4096
	s_waitcnt lgkmcnt(2)
	v_mfma_f32_32x32x16_bf16 v[64:79], v[228:231], v[240:243], v[64:79]
	ds_read_b128 v[228:231], v199
	ds_read_b128 v[244:247], v200
	s_waitcnt lgkmcnt(0)
	v_mfma_f32_32x32x16_bf16 v[64:79], v[228:231], v[244:247], v[64:79]
	ds_read_b128 v[228:231], v201
	s_waitcnt lgkmcnt(0)
	v_mfma_f32_32x32x16_bf16 v[64:79], v[228:231], v[232:235], v[64:79]
	ds_read_b128 v[226:229], v197 offset:4096
	s_waitcnt lgkmcnt(0)
	v_mfma_f32_32x32x16_bf16 v[80:95], v[226:229], v[240:243], v[80:95]
	ds_read_b128 v[240:243], v201 offset:4096
	v_cvt_pk_bf16_f32 v154, v155, v209
	v_cvt_pk_bf16_f32 v155, v210, v211
	s_nop 0
	v_permlane32_swap_b32_e32 v152, v154
	v_permlane32_swap_b32_e32 v153, v155
	v_mfma_f32_32x32x16_bf16 v[80:95], v[236:239], v[244:247], v[80:95]
	s_nop 1
	v_cndmask_b32_e32 v229, v72, v208, vcc
	v_cndmask_b32_e32 v227, v76, v208, vcc
	v_cndmask_b32_e32 v228, v73, v208, vcc
	s_waitcnt lgkmcnt(0)
	v_mfma_f32_32x32x16_bf16 v[80:95], v[240:243], v[232:235], v[80:95]
	s_nop 11
	v_cndmask_b32_e32 v73, v95, v208, vcc
	v_cndmask_b32_e32 v226, v74, v208, vcc
	v_cndmask_b32_e32 v172, v79, v208, vcc
	v_cndmask_b32_e32 v173, v78, v208, vcc
	v_cndmask_b32_e32 v223, v77, v208, vcc
	v_cndmask_b32_e32 v225, v75, v208, vcc
	v_cndmask_b32_e32 v72, v94, v208, vcc
	v_cndmask_b32_e32 v75, v93, v208, vcc
	v_cndmask_b32_e32 v74, v92, v208, vcc
	v_cndmask_b32_e32 v77, v91, v208, vcc
	v_cndmask_b32_e32 v76, v90, v208, vcc
	v_cndmask_b32_e32 v79, v89, v208, vcc
	v_cndmask_b32_e32 v78, v88, v208, vcc
	v_cndmask_b32_e32 v87, v87, v208, vcc
	v_cndmask_b32_e32 v86, v86, v208, vcc
	v_cndmask_b32_e32 v85, v85, v208, vcc
	v_cndmask_b32_e32 v84, v84, v208, vcc
	v_cndmask_b32_e32 v83, v83, v208, vcc
	v_cndmask_b32_e32 v82, v82, v208, vcc
	v_cndmask_b32_e32 v81, v81, v208, vcc
	v_cndmask_b32_e32 v80, v80, v208, vcc
	global_load_dwordx4 v[90:93], v162, s[36:37] offset:3456
	global_load_dwordx4 v[156:159], v164, s[36:37] offset:3456
	ds_read_b128 v[230:233], v177 offset:16384
	ds_read_b128 v[234:237], v161 offset:16384
	ds_read_b128 v[238:241], v180 offset:16384
	v_max_f32_e32 v88, v65, v65
	v_max_f32_e32 v89, v64, v64
	s_waitcnt lgkmcnt(2)
	v_mfma_f32_32x32x16_bf16 v[16:31], v[140:143], v[230:233], v[16:31]
	ds_read_b128 v[230:233], v177 offset:20480
	v_max_f32_e32 v88, v89, v88
	v_max3_f32 v88, v88, v66, v67
	v_max3_f32 v88, v88, v68, v69
	ds_read_b128 v[242:245], v179 offset:16384
	v_max3_f32 v88, v88, v70, v71
	v_max3_f32 v88, v88, v229, v228
	s_waitcnt lgkmcnt(1)
	v_mfma_f32_32x32x16_bf16 v[48:63], v[140:143], v[230:233], v[48:63]
	ds_read_b128 v[230:233], v177 offset:24576
	v_max3_f32 v88, v88, v226, v225
	v_max3_f32 v88, v88, v227, v223
	v_max3_f32 v88, v88, v173, v172
	v_max3_f32 v88, v88, v80, v81
	v_max3_f32 v88, v88, v82, v83
	v_max3_f32 v88, v88, v84, v85
	v_mfma_f32_32x32x16_bf16 v[16:31], v[144:147], v[234:237], v[16:31]
	ds_read_b128 v[234:237], v161 offset:20480
	v_max3_f32 v88, v88, v86, v87
	v_max3_f32 v88, v88, v78, v79
	v_max3_f32 v88, v88, v76, v77
	v_max3_f32 v88, v88, v74, v75
	v_max3_f32 v88, v88, v72, v73
	v_mov_b32_e32 v89, v88
	s_waitcnt lgkmcnt(1)
	v_mfma_f32_32x32x16_bf16 v[32:47], v[140:143], v[230:233], v[32:47]
	ds_read_b128 v[230:233], v177 offset:28672
	v_permlane32_swap_b32_e32 v88, v89
	v_max_f32_e32 v89, v89, v89
	v_max_f32_e32 v88, v88, v88
	v_max_f32_e32 v88, v88, v89
	v_sub_f32_e32 v89, v88, v222
	s_waitcnt lgkmcnt(1)
	v_mfma_f32_32x32x16_bf16 v[48:63], v[144:147], v[234:237], v[48:63]
	ds_read_b128 v[234:237], v161 offset:24576
	v_cmp_ge_f32_e32 vcc, s91, v89
	v_max_f32_e32 v89, v222, v222
	v_max_f32_e32 v89, v89, v88
	v_sub_f32_e32 v88, v222, v89
	v_mul_f32_e32 v88, 0x3dd53b94, v88
	v_exp_f32_e32 v88, v88
	s_waitcnt lgkmcnt(1)
	v_mfma_f32_32x32x16_bf16 v[0:15], v[140:143], v[230:233], v[0:15]
	s_cmp_eq_u64 vcc, exec
	s_cselect_b64 s[8:9], -1, 0
	v_cndmask_b32_e64 v88, v88, 1.0, s[8:9]
	v_cmp_gt_f32_e32 vcc, 1.0, v88
	v_mfma_f32_32x32x16_bf16 v[16:31], v[148:151], v[238:241], v[16:31]
	ds_read_b128 v[238:241], v180 offset:20480
	s_waitcnt lgkmcnt(1)
	v_mfma_f32_32x32x16_bf16 v[32:47], v[144:147], v[234:237], v[32:47]
	ds_read_b128 v[234:237], v161 offset:28672
	s_waitcnt lgkmcnt(1)
	v_mfma_f32_32x32x16_bf16 v[48:63], v[148:151], v[238:241], v[48:63]
	ds_read_b128 v[238:241], v180 offset:24576
	s_waitcnt lgkmcnt(1)
	v_mfma_f32_32x32x16_bf16 v[0:15], v[144:147], v[234:237], v[0:15]
	v_mfma_f32_32x32x16_bf16 v[16:31], v[152:155], v[242:245], v[16:31]
	ds_read_b128 v[242:245], v179 offset:20480
	s_waitcnt lgkmcnt(1)
	v_mfma_f32_32x32x16_bf16 v[32:47], v[148:151], v[238:241], v[32:47]
	ds_read_b128 v[238:241], v180 offset:28672
	s_waitcnt lgkmcnt(1)
	v_mfma_f32_32x32x16_bf16 v[48:63], v[152:155], v[242:245], v[48:63]
	ds_read_b128 v[242:245], v179 offset:24576
	s_waitcnt lgkmcnt(1)
	v_mfma_f32_32x32x16_bf16 v[0:15], v[148:151], v[238:241], v[0:15]
	s_waitcnt lgkmcnt(0)
	v_mfma_f32_32x32x16_bf16 v[32:47], v[152:155], v[242:245], v[32:47]
	ds_read_b128 v[242:245], v179 offset:28672
	s_waitcnt vmcnt(2)
	ds_write_b128 v184, v[128:131] offset:49152
	ds_write_b128 v184, v[132:135] offset:57344
	ds_write_b128 v203, v[136:139]
	s_waitcnt lgkmcnt(0)
	s_barrier
	v_mfma_f32_32x32x16_bf16 v[0:15], v[152:155], v[242:245], v[0:15]
	s_waitcnt vmcnt(0)
	ds_write_b128 v185, v[90:93] offset:16384
	ds_write_b128 v185, v[156:159] offset:24576
	s_cbranch_vccnz .Lresc_b

.Lresc_a:
	s_and_saveexec_b64 s[14:15], s[6:7]
	ds_write_b32 v181, v224 offset:128
	s_or_b64 exec, exec, s[14:15]
	s_waitcnt lgkmcnt(0)
	v_add_u32_e32 v141, v178, v160
	ds_read_b128 v[128:131], v141 offset:224
	ds_read_b128 v[132:135], v141 offset:192
	ds_read_b128 v[136:139], v141 offset:160
	ds_read_b128 v[142:145], v141 offset:128
	s_waitcnt lgkmcnt(3)
	v_pk_mul_f32 v[28:29], v[28:29], v[128:129]
	s_waitcnt lgkmcnt(2)
	v_pk_mul_f32 v[24:25], v[24:25], v[132:133]
	s_waitcnt lgkmcnt(1)
	v_pk_mul_f32 v[20:21], v[20:21], v[136:137]
	v_pk_mul_f32 v[30:31], v[30:31], v[130:131]
	v_pk_mul_f32 v[26:27], v[26:27], v[134:135]
	v_pk_mul_f32 v[22:23], v[22:23], v[138:139]
	s_waitcnt lgkmcnt(0)
	v_pk_mul_f32 v[18:19], v[18:19], v[144:145]
	v_pk_mul_f32 v[16:17], v[16:17], v[142:143]
	v_pk_mul_f32 v[60:61], v[60:61], v[128:129]
	v_pk_mul_f32 v[56:57], v[56:57], v[132:133]
	v_pk_mul_f32 v[52:53], v[52:53], v[136:137]
	v_pk_mul_f32 v[62:63], v[62:63], v[130:131]
	v_pk_mul_f32 v[58:59], v[58:59], v[134:135]
	v_pk_mul_f32 v[54:55], v[54:55], v[138:139]
	v_pk_mul_f32 v[50:51], v[50:51], v[144:145]
	v_pk_mul_f32 v[48:49], v[48:49], v[142:143]
	v_pk_mul_f32 v[44:45], v[44:45], v[128:129]
	v_pk_mul_f32 v[40:41], v[40:41], v[132:133]
	v_pk_mul_f32 v[36:37], v[36:37], v[136:137]
	v_pk_mul_f32 v[46:47], v[46:47], v[130:131]
	v_pk_mul_f32 v[42:43], v[42:43], v[134:135]
	v_pk_mul_f32 v[38:39], v[38:39], v[138:139]
	v_pk_mul_f32 v[34:35], v[34:35], v[144:145]
	v_pk_mul_f32 v[32:33], v[32:33], v[142:143]
	v_pk_mul_f32 v[12:13], v[12:13], v[128:129]
	v_pk_mul_f32 v[8:9], v[8:9], v[132:133]
	v_pk_mul_f32 v[4:5], v[4:5], v[136:137]
	v_pk_mul_f32 v[14:15], v[14:15], v[130:131]
	v_pk_mul_f32 v[10:11], v[10:11], v[134:135]
	v_pk_mul_f32 v[6:7], v[6:7], v[138:139]
	v_pk_mul_f32 v[2:3], v[2:3], v[144:145]
	v_pk_mul_f32 v[0:1], v[0:1], v[142:143]
	s_branch .LBB0_985
.Lresc_b:
	s_and_saveexec_b64 s[14:15], s[6:7]
	ds_write_b32 v181, v88 offset:128
	s_or_b64 exec, exec, s[14:15]
	s_waitcnt lgkmcnt(0)
	v_add_u32_e32 v94, v178, v160
	ds_read_b128 v[90:93], v94 offset:224
	ds_read_b128 v[128:131], v94 offset:192
	ds_read_b128 v[132:135], v94 offset:160
	ds_read_b128 v[136:139], v94 offset:128
	s_waitcnt lgkmcnt(3)
	v_pk_mul_f32 v[28:29], v[28:29], v[90:91]
	s_waitcnt lgkmcnt(2)
	v_pk_mul_f32 v[24:25], v[24:25], v[128:129]
	s_waitcnt lgkmcnt(1)
	v_pk_mul_f32 v[20:21], v[20:21], v[132:133]
	v_pk_mul_f32 v[30:31], v[30:31], v[92:93]
	v_pk_mul_f32 v[26:27], v[26:27], v[130:131]
	v_pk_mul_f32 v[22:23], v[22:23], v[134:135]
	s_waitcnt lgkmcnt(0)
	v_pk_mul_f32 v[18:19], v[18:19], v[138:139]
	v_pk_mul_f32 v[16:17], v[16:17], v[136:137]
	v_pk_mul_f32 v[60:61], v[60:61], v[90:91]
	v_pk_mul_f32 v[56:57], v[56:57], v[128:129]
	v_pk_mul_f32 v[52:53], v[52:53], v[132:133]
	v_pk_mul_f32 v[62:63], v[62:63], v[92:93]
	v_pk_mul_f32 v[58:59], v[58:59], v[130:131]
	v_pk_mul_f32 v[54:55], v[54:55], v[134:135]
	v_pk_mul_f32 v[50:51], v[50:51], v[138:139]
	v_pk_mul_f32 v[48:49], v[48:49], v[136:137]
	v_pk_mul_f32 v[44:45], v[44:45], v[90:91]
	v_pk_mul_f32 v[40:41], v[40:41], v[128:129]
	v_pk_mul_f32 v[36:37], v[36:37], v[132:133]
	v_pk_mul_f32 v[46:47], v[46:47], v[92:93]
	v_pk_mul_f32 v[42:43], v[42:43], v[130:131]
	v_pk_mul_f32 v[38:39], v[38:39], v[134:135]
	v_pk_mul_f32 v[34:35], v[34:35], v[138:139]
	v_pk_mul_f32 v[32:33], v[32:33], v[136:137]
	v_pk_mul_f32 v[12:13], v[12:13], v[90:91]
	v_pk_mul_f32 v[8:9], v[8:9], v[128:129]
	v_pk_mul_f32 v[4:5], v[4:5], v[132:133]
	v_pk_mul_f32 v[14:15], v[14:15], v[92:93]
	v_pk_mul_f32 v[10:11], v[10:11], v[130:131]
	v_pk_mul_f32 v[6:7], v[6:7], v[134:135]
	v_pk_mul_f32 v[2:3], v[2:3], v[138:139]
	v_pk_mul_f32 v[0:1], v[0:1], v[136:137]
	s_branch .LBB0_989
